# mode-3 (down/out-proj) K-loop load segments also made VALU-free (saddr LDS-DMA, precomputed B-fragment base), in addition to mode 0
# speedup vs baseline: 1.0305x; 1.0083x over previous
; __device__ __forceinline__ int otid() { int t = threadIdx.x; asm volatile("" : "+v"(t)); return t; }
; #define PG8_STAGE(bufoff, gbase, voff) do { _Pragma("unroll") for (int _i = 0; _i < 2; ++_i) \
;         __builtin_amdgcn_global_load_lds((const unsigned*)((const char*)(gbase) + (voff)[_i]), (LAS unsigned*)(lds + (bufoff) + ldsw + _i * 8192), 16, 0, 0); } while (0)
; #define PG8_WAIT_V(n) asm volatile("s_waitcnt vmcnt(" #n ")" ::: "memory")
; #define PG8_BAR __builtin_amdgcn_s_barrier()
; template <int MODE, class EpiT, class Sched>
; __device__ __forceinline__ void gemm_phase(LAS unsigned char* lds, const Gemm g, const Sched& S, const EpiT& E) {
;     const int tid = otid(), wid = __builtin_amdgcn_readfirstlane(tid >> 6), lane = tid & 63, wr = wid >> 2, wc = wid & 3, fr = lane & 15, fq = lane >> 4;
;     const int K = g.K, nt = K / BK;
;     unsigned voffA[2], voffB[2];
; #pragma unroll
;     for (int i = 0; i < 2; ++i) { int R, C; stage_rc(tid * 16 + i * 8192, R, C); voffA[i] = (unsigned)(R * K + C) * 2u; voffB[i] = (unsigned)(R * K + C) * 2u; }
;     const size_t kstep = (size_t)(BK * 2);
;     const size_t hstep = (size_t)HALF * K * 2;
;     const size_t tstep = 2 * hstep;
;     const unsigned ldsw = (unsigned)wid * 1024u;
;     const int aoff = lds_byte(wr * 64 + fr, fq * 8), boff = lds_byte(wc * 32 + fr, fq * 8);
;     ...
;     PG8_STAGE(PG8_SB(0, 0), cB, voffB); PG8_STAGE(PG8_SA(0, 0), cA, voffA); PG8_STAGE(PG8_SB(0, 1), cB + hstep, voffB); PG8_STAGE(PG8_SA(0, 1), cA + hstep, voffA);
;     if (wr == 1) PG8_BAR;
;     PG8_WAIT_V(4); PG8_BAR;
;     PG8_STAGE(PG8_SB(1, 0), cB + kstep, voffB); PG8_STAGE(PG8_SA(1, 0), cA + kstep, voffA); PG8_STAGE(PG8_SB(1, 1), cB + hstep + kstep, voffB);
;     PG8_WAIT_V(6); PG8_BAR;
.LBB0_186:
	s_add_i32 m0, s21, 0x18000
	v_lshl_add_u64 v[2:3], v[2:3], 0, s[76:77]
	s_waitcnt vmcnt(4)
	s_barrier
	global_load_lds_dwordx4 v[2:3], off
	v_lshl_add_u64 v[2:3], v[4:5], 0, s[76:77]
	s_add_i32 m0, s21, 0x1a000
	s_add_i32 s61, s21, 0x8000
	global_load_lds_dwordx4 v[2:3], off
	v_lshl_add_u64 v[2:3], v[6:7], 0, s[76:77]
	s_mov_b32 m0, s61
	s_add_i32 s74, s21, 0xa000
	global_load_lds_dwordx4 v[2:3], off
	v_lshl_add_u64 v[2:3], v[8:9], 0, s[76:77]
	s_mov_b32 m0, s74
	s_lshl_b32 s22, s14, 2
	global_load_lds_dwordx4 v[2:3], off
	s_add_i32 m0, s21, 0x1c000
	v_lshl_add_u64 v[2:3], v[10:11], 0, s[76:77]
	global_load_lds_dwordx4 v[2:3], off
	v_lshl_add_u64 v[2:3], v[12:13], 0, s[76:77]
	s_add_i32 m0, s21, 0x1e000
	v_bfe_u32 v21, v20, 4, 2
	global_load_lds_dwordx4 v[2:3], off
	v_cvt_f32_u32_e32 v2, s22
	v_and_b32_e32 v22, 15, v20
	v_lshlrev_b32_e32 v24, 4, v21
	v_lshlrev_b32_e32 v20, 2, v20
	v_rcp_iflag_f32_e32 v2, v2
	s_and_b32 s57, s2, 3
	v_lshl_or_b32 v181, s3, 6, v22
	v_lshl_or_b32 v22, v22, 6, v24
	v_mul_f32_e32 v2, 0x4f7ffffe, v2
	v_cvt_u32_f32_e32 v2, v2
	s_lshl_b32 s2, s3, 13
	v_and_b32_e32 v20, 32, v20
	s_lshr_b32 s60, s16, 6
	v_bitop3_b32 v24, v22, s2, v20 bitop3:0xde
	s_lshl_b32 s2, s57, 12
	v_bitop3_b32 v194, v22, s2, v20 bitop3:0xde
	v_add_u32_e32 v249, 0x10000, v194
	s_add_i32 s75, s60, -2
	s_ashr_i32 s3, s31, 31
	s_lshl_b32 s2, s14, 3
	s_cmp_lg_u64 s[12:13], 0
	v_readfirstlane_b32 s30, v2
	v_add_u32_e32 v2, v16, v14
	s_cselect_b64 s[78:79], -1, 0
	s_sub_i32 s23, 0, s22
	v_add_lshl_u32 v2, v2, v15, 1
	v_mov_b32_e32 v3, v1
	s_waitcnt vmcnt(6)
	s_mul_i32 s23, s23, s30
	v_lshl_add_u64 v[176:177], s[38:39], 0, v[2:3]
	v_add_u32_e32 v2, v19, v17
	v_lshlrev_b32_e32 v23, 3, v21
	s_mul_hi_u32 s23, s30, s23
	v_add_lshl_u32 v2, v2, v18, 1
	v_lshl_or_b32 v195, s57, 5, v23
	s_mov_b32 s88, 0
	v_cmp_eq_u32_e64 s[40:41], 0, v21
	s_mov_b32 s73, s25
	s_add_i32 s23, s30, s23
	v_lshl_add_u64 v[182:183], s[38:39], 0, v[2:3]
	v_add_u32_e32 v196, 0, v24
	s_barrier
	s_branch .LBB0_188

; #define PG8_STAGE(bufoff, gbase, voff) do { _Pragma("unroll") for (int _i = 0; _i < 2; ++_i) \
;         __builtin_amdgcn_global_load_lds((const unsigned*)((const char*)(gbase) + (voff)[_i]), (LAS unsigned*)(lds + (bufoff) + ldsw + _i * 8192), 16, 0, 0); } while (0)
; #define PG8_LDA(dst, b, h) do { _Pragma("unroll") for (int m = 0; m < 4; ++m) _Pragma("unroll") for (int k = 0; k < 2; ++k) dst[m][k] = *(const LAS bf16x8*)(lds + PG8_SA(b, h) + aoff + m * 2048 + k * 1024); } while (0)
; #define PG8_LDB(dst, b, h) do { _Pragma("unroll") for (int n = 0; n < 2; ++n) _Pragma("unroll") for (int k = 0; k < 2; ++k) dst[n][k] = *(const LAS bf16x8*)(lds + PG8_SB(b, h) + boff + n * 2048 + k * 1024); } while (0)
; #define PG8_MMA(ai, bj, At, Bt) do { __builtin_amdgcn_s_setprio(1); _Pragma("unroll") for (int m = 0; m < 4; ++m) _Pragma("unroll") for (int n = 0; n < 2; ++n) _Pragma("unroll") for (int k = 0; k < 2; ++k) \
;         acc[ai][bj][m][n] = __builtin_amdgcn_mfma_f32_16x16x32_bf16(Bt[n][k], At[m][k], acc[ai][bj][m][n], 0, 0, 0); __builtin_amdgcn_s_setprio(0); } while (0)
; #define PG8_WAIT_V(n) asm volatile("s_waitcnt vmcnt(" #n ")" ::: "memory")
; #define PG8_WAIT_L(n) asm volatile("s_waitcnt lgkmcnt(" #n ")" ::: "memory")
; template <int MODE, class EpiT, class Sched>
; __device__ __forceinline__ void gemm_phase(LAS unsigned char* lds, const Gemm g, const Sched& S, const EpiT& E) {
;     ...
;         for (int t = 0; t < nt; t += 2) {
;             const bool last = (t == nt - 2);
;             const char* a1 = cA + (size_t)(t + 1) * kstep;
;             const char* a2 = last ? nA : cA + (size_t)(t + 2) * kstep; const char* b2 = last ? nB : cB + (size_t)(t + 2) * kstep;
;             const char* a3 = a2 + kstep; const char* b3 = b2 + kstep;
;             PG8_LDB(B0, 0, 0); PG8_SCHED; PG8_LDA(At, 0, 0); PG8_STAGE(PG8_SA(1, 1), a1 + hstep, voffA);
;             PG8_WAIT_L(8); PG8_BAR; PG8_WAIT_L(0); PG8_MMA(0, 0, At, B0); PG8_BAR; PG8_SCHED;
;             PG8_LDB(B1, 0, 1); PG8_STAGE(PG8_SB(0, 0), b2, voffB);
;             PG8_BAR; PG8_WAIT_L(0); PG8_MMA(0, 1, At, B1); PG8_BAR;
;             PG8_LDA(At, 0, 1); PG8_STAGE(PG8_SA(0, 0), a2, voffA);
;             PG8_BAR; PG8_WAIT_L(0); PG8_MMA(1, 0, At, B0); PG8_BAR; PG8_SCHED;
;             PG8_STAGE(PG8_SB(0, 1), b2 + hstep, voffB);
;             PG8_WAIT_V(6); PG8_BAR; PG8_MMA(1, 1, At, B1); PG8_BAR;
.LBB0_195:
	s_add_i32 vcc_lo, s44, 2
	s_add_u32 s52, s4, 0x80
	s_addc_u32 s45, s5, 0
	s_add_u32 s100, s4, s38
	s_addc_u32 s101, s5, 0
	s_add_i32 s58, 0, 0x10000
	ds_read_b128 v[58:61], v249
	ds_read_b128 v[62:65], v249 offset:1024
	ds_read_b128 v[70:73], v249 offset:2048
	ds_read_b128 v[74:77], v249 offset:3072
	s_cmp_eq_u32 s75, s44
	s_cselect_b32 s44, s68, s52
	s_cselect_b32 s45, s69, s45
	s_cselect_b32 s53, s47, s90
	s_cselect_b32 s52, s46, s89
	s_add_i32 m0, s21, 0xc000
	ds_read_b128 v[138:141], v196
	ds_read_b128 v[142:145], v196 offset:1024
	ds_read_b128 v[146:149], v196 offset:2048
	ds_read_b128 v[150:153], v196 offset:3072
	ds_read_b128 v[162:165], v196 offset:4096
	ds_read_b128 v[166:169], v196 offset:5120
	ds_read_b128 v[170:173], v196 offset:6144
	ds_read_b128 v[184:187], v196 offset:7168
	global_load_lds_dwordx4 v0, s[100:101]
	s_add_i32 m0, s21, 0xe000
	s_nop 0
	global_load_lds_dwordx4 v174, s[100:101]
	s_waitcnt lgkmcnt(8)
	s_barrier
	s_waitcnt lgkmcnt(0)
	v_mfma_f32_16x16x32_bf16 v[158:161], v[58:61], v[138:141], v[158:161]
	v_mfma_f32_16x16x32_bf16 v[154:157], v[70:73], v[138:141], v[154:157]
	v_mfma_f32_16x16x32_bf16 v[126:129], v[58:61], v[146:149], v[126:129]
	v_mfma_f32_16x16x32_bf16 v[122:125], v[70:73], v[146:149], v[122:125]
	v_mfma_f32_16x16x32_bf16 v[110:113], v[58:61], v[162:165], v[110:113]
	v_mfma_f32_16x16x32_bf16 v[106:109], v[70:73], v[162:165], v[106:109]
	v_mfma_f32_16x16x32_bf16 v[94:97], v[58:61], v[170:173], v[94:97]
	v_mfma_f32_16x16x32_bf16 v[90:93], v[70:73], v[170:173], v[90:93]
	v_mfma_f32_16x16x32_bf16 v[158:161], v[62:65], v[142:145], v[158:161]
	v_mfma_f32_16x16x32_bf16 v[154:157], v[74:77], v[142:145], v[154:157]
	v_mfma_f32_16x16x32_bf16 v[126:129], v[62:65], v[150:153], v[126:129]
	v_mfma_f32_16x16x32_bf16 v[122:125], v[74:77], v[150:153], v[122:125]
	v_mfma_f32_16x16x32_bf16 v[110:113], v[62:65], v[166:169], v[110:113]
	v_mfma_f32_16x16x32_bf16 v[106:109], v[74:77], v[166:169], v[106:109]
	v_mfma_f32_16x16x32_bf16 v[94:97], v[62:65], v[184:187], v[94:97]
	v_mfma_f32_16x16x32_bf16 v[90:93], v[74:77], v[184:187], v[90:93]
	s_barrier
	s_add_i32 s59, 0, 0x14000
	s_add_i32 s58, s58, s20
	ds_read_b128 v[188:191], v249 offset:16384
	ds_read_b128 v[220:223], v249 offset:17408
	ds_read_b128 v[224:227], v249 offset:18432
	ds_read_b128 v[228:231], v249 offset:19456
	s_add_u32 s98, s52, 0x80
	s_addc_u32 s99, s53, 0
	s_mov_b32 m0, s58
	s_nop 0
	global_load_lds_dwordx4 v0, s[52:53]
	s_add_i32 m0, s58, 0x2000
	s_nop 0
	global_load_lds_dwordx4 v174, s[52:53]
	s_barrier
	s_waitcnt lgkmcnt(0)
	v_mfma_f32_16x16x32_bf16 v[134:137], v[188:191], v[138:141], v[134:137]
	v_mfma_f32_16x16x32_bf16 v[130:133], v[224:227], v[138:141], v[130:133]
	v_mfma_f32_16x16x32_bf16 v[118:121], v[188:191], v[146:149], v[118:121]
	v_mfma_f32_16x16x32_bf16 v[114:117], v[224:227], v[146:149], v[114:117]
	v_mfma_f32_16x16x32_bf16 v[102:105], v[188:191], v[162:165], v[102:105]
	v_mfma_f32_16x16x32_bf16 v[98:101], v[224:227], v[162:165], v[98:101]
	v_mfma_f32_16x16x32_bf16 v[86:89], v[188:191], v[170:173], v[86:89]
	v_mfma_f32_16x16x32_bf16 v[82:85], v[224:227], v[170:173], v[82:85]
	v_mfma_f32_16x16x32_bf16 v[134:137], v[220:223], v[142:145], v[134:137]
	v_mfma_f32_16x16x32_bf16 v[130:133], v[228:231], v[142:145], v[130:133]
	v_mfma_f32_16x16x32_bf16 v[118:121], v[220:223], v[150:153], v[118:121]
	v_mfma_f32_16x16x32_bf16 v[114:117], v[228:231], v[150:153], v[114:117]
	v_mfma_f32_16x16x32_bf16 v[102:105], v[220:223], v[166:169], v[102:105]
	v_mfma_f32_16x16x32_bf16 v[98:101], v[228:231], v[166:169], v[98:101]
	v_mfma_f32_16x16x32_bf16 v[86:89], v[220:223], v[184:187], v[86:89]
	v_mfma_f32_16x16x32_bf16 v[82:85], v[228:231], v[184:187], v[82:85]
	s_barrier
	s_mov_b32 m0, s21
	s_add_u32 s100, s44, 0x80
	s_addc_u32 s101, s45, 0
	ds_read_b128 v[138:141], v196 offset:16384
	ds_read_b128 v[142:145], v196 offset:17408
	ds_read_b128 v[146:149], v196 offset:18432
	ds_read_b128 v[150:153], v196 offset:19456
	ds_read_b128 v[162:165], v196 offset:20480
	ds_read_b128 v[166:169], v196 offset:21504
	ds_read_b128 v[170:173], v196 offset:22528
	ds_read_b128 v[184:187], v196 offset:23552
	global_load_lds_dwordx4 v0, s[44:45]
	s_mov_b32 m0, s50
	s_nop 0
	global_load_lds_dwordx4 v174, s[44:45]
	s_barrier
	s_waitcnt lgkmcnt(0)
	v_mfma_f32_16x16x32_bf16 v[78:81], v[58:61], v[138:141], v[78:81]
	v_mfma_f32_16x16x32_bf16 v[66:69], v[70:73], v[138:141], v[66:69]
	v_mfma_f32_16x16x32_bf16 v[46:49], v[58:61], v[146:149], v[46:49]
	v_mfma_f32_16x16x32_bf16 v[42:45], v[70:73], v[146:149], v[42:45]
	v_mfma_f32_16x16x32_bf16 v[30:33], v[58:61], v[162:165], v[30:33]
	v_mfma_f32_16x16x32_bf16 v[26:29], v[70:73], v[162:165], v[26:29]
	v_mfma_f32_16x16x32_bf16 v[14:17], v[58:61], v[170:173], v[14:17]
	v_mfma_f32_16x16x32_bf16 v[10:13], v[70:73], v[170:173], v[10:13]
	v_mfma_f32_16x16x32_bf16 v[78:81], v[62:65], v[142:145], v[78:81]
	v_mfma_f32_16x16x32_bf16 v[66:69], v[74:77], v[142:145], v[66:69]
	v_mfma_f32_16x16x32_bf16 v[46:49], v[62:65], v[150:153], v[46:49]
	v_mfma_f32_16x16x32_bf16 v[42:45], v[74:77], v[150:153], v[42:45]
	v_mfma_f32_16x16x32_bf16 v[30:33], v[62:65], v[166:169], v[30:33]
	v_mfma_f32_16x16x32_bf16 v[26:29], v[74:77], v[166:169], v[26:29]
	v_mfma_f32_16x16x32_bf16 v[14:17], v[62:65], v[184:187], v[14:17]
	v_mfma_f32_16x16x32_bf16 v[10:13], v[74:77], v[184:187], v[10:13]
	s_barrier
	s_add_u32 s52, s52, s38
	s_addc_u32 s53, s53, 0
	s_add_i32 s58, s59, s20
	s_mov_b32 m0, s58
	s_nop 0
	global_load_lds_dwordx4 v0, s[52:53]
	s_add_i32 m0, s58, 0x2000
	s_nop 0
	global_load_lds_dwordx4 v174, s[52:53]
	s_waitcnt vmcnt(6)
	s_barrier
; #define PG8_STAGE(bufoff, gbase, voff) do { _Pragma("unroll") for (int _i = 0; _i < 2; ++_i) \
;         __builtin_amdgcn_global_load_lds((const unsigned*)((const char*)(gbase) + (voff)[_i]), (LAS unsigned*)(lds + (bufoff) + ldsw + _i * 8192), 16, 0, 0); } while (0)
; #define PG8_LDA(dst, b, h) do { _Pragma("unroll") for (int m = 0; m < 4; ++m) _Pragma("unroll") for (int k = 0; k < 2; ++k) dst[m][k] = *(const LAS bf16x8*)(lds + PG8_SA(b, h) + aoff + m * 2048 + k * 1024); } while (0)
; #define PG8_LDB(dst, b, h) do { _Pragma("unroll") for (int n = 0; n < 2; ++n) _Pragma("unroll") for (int k = 0; k < 2; ++k) dst[n][k] = *(const LAS bf16x8*)(lds + PG8_SB(b, h) + boff + n * 2048 + k * 1024); } while (0)
; #define PG8_MMA(ai, bj, At, Bt) do { __builtin_amdgcn_s_setprio(1); _Pragma("unroll") for (int m = 0; m < 4; ++m) _Pragma("unroll") for (int n = 0; n < 2; ++n) _Pragma("unroll") for (int k = 0; k < 2; ++k) \
;         acc[ai][bj][m][n] = __builtin_amdgcn_mfma_f32_16x16x32_bf16(Bt[n][k], At[m][k], acc[ai][bj][m][n], 0, 0, 0); __builtin_amdgcn_s_setprio(0); } while (0)
; #define PG8_WAIT_V(n) asm volatile("s_waitcnt vmcnt(" #n ")" ::: "memory")
; #define PG8_WAIT_L(n) asm volatile("s_waitcnt lgkmcnt(" #n ")" ::: "memory")
; #define PG8_BAR __builtin_amdgcn_s_barrier()
; #define PG8_SCHED __builtin_amdgcn_sched_barrier(0)
; template <int MODE, class EpiT, class Sched>
; __device__ __forceinline__ void gemm_phase(LAS unsigned char* lds, const Gemm g, const Sched& S, const EpiT& E) {
;     ...
;             PG8_WAIT_V(6); PG8_BAR; PG8_MMA(1, 1, At, B1); PG8_BAR;
;             PG8_LDB(B0, 1, 0); PG8_SCHED; PG8_LDA(At, 1, 0); PG8_STAGE(PG8_SA(0, 1), a2 + hstep, voffA);
;             PG8_WAIT_L(8); PG8_BAR; PG8_WAIT_L(0); PG8_MMA(0, 0, At, B0); PG8_BAR; PG8_SCHED;
;             PG8_LDB(B1, 1, 1); PG8_STAGE(PG8_SB(1, 0), b3, voffB);
;             PG8_BAR; PG8_WAIT_L(0); PG8_MMA(0, 1, At, B1); PG8_BAR;
;             PG8_LDA(At, 1, 1); PG8_STAGE(PG8_SA(1, 0), a3, voffA);
;             PG8_BAR; PG8_WAIT_L(0); PG8_MMA(1, 0, At, B0); PG8_BAR; PG8_SCHED;
	v_mfma_f32_16x16x32_bf16 v[54:57], v[188:191], v[138:141], v[54:57]
	v_mfma_f32_16x16x32_bf16 v[50:53], v[224:227], v[138:141], v[50:53]
	v_mfma_f32_16x16x32_bf16 v[38:41], v[188:191], v[146:149], v[38:41]
	v_mfma_f32_16x16x32_bf16 v[34:37], v[224:227], v[146:149], v[34:37]
	v_mfma_f32_16x16x32_bf16 v[22:25], v[188:191], v[162:165], v[22:25]
	v_mfma_f32_16x16x32_bf16 v[18:21], v[224:227], v[162:165], v[18:21]
	v_mfma_f32_16x16x32_bf16 v[6:9], v[188:191], v[170:173], v[6:9]
	v_mfma_f32_16x16x32_bf16 v[2:5], v[224:227], v[170:173], v[2:5]
	v_mfma_f32_16x16x32_bf16 v[54:57], v[220:223], v[142:145], v[54:57]
	v_mfma_f32_16x16x32_bf16 v[50:53], v[228:231], v[142:145], v[50:53]
	v_mfma_f32_16x16x32_bf16 v[38:41], v[220:223], v[150:153], v[38:41]
	v_mfma_f32_16x16x32_bf16 v[34:37], v[228:231], v[150:153], v[34:37]
	v_mfma_f32_16x16x32_bf16 v[22:25], v[220:223], v[166:169], v[22:25]
	v_mfma_f32_16x16x32_bf16 v[18:21], v[228:231], v[166:169], v[18:21]
	v_mfma_f32_16x16x32_bf16 v[6:9], v[220:223], v[184:187], v[6:9]
	v_mfma_f32_16x16x32_bf16 v[2:5], v[228:231], v[184:187], v[2:5]
	s_barrier
	s_add_i32 s52, 0, 0x18000
	ds_read_b128 v[58:61], v249 offset:32768
	ds_read_b128 v[62:65], v249 offset:33792
	ds_read_b128 v[70:73], v249 offset:34816
	ds_read_b128 v[74:77], v249 offset:35840
	s_add_u32 s44, s44, s38
	s_addc_u32 s45, s45, 0
	s_mov_b32 m0, s51
	ds_read_b128 v[138:141], v196 offset:32768
	ds_read_b128 v[142:145], v196 offset:33792
	ds_read_b128 v[146:149], v196 offset:34816
	ds_read_b128 v[150:153], v196 offset:35840
	ds_read_b128 v[162:165], v196 offset:36864
	ds_read_b128 v[166:169], v196 offset:37888
	ds_read_b128 v[170:173], v196 offset:38912
	ds_read_b128 v[184:187], v196 offset:39936
	global_load_lds_dwordx4 v0, s[44:45]
	s_mov_b32 m0, s56
	s_nop 0
	global_load_lds_dwordx4 v174, s[44:45]
	s_waitcnt lgkmcnt(8)
	s_barrier
	s_waitcnt lgkmcnt(0)
	v_mfma_f32_16x16x32_bf16 v[158:161], v[58:61], v[138:141], v[158:161]
	v_mfma_f32_16x16x32_bf16 v[154:157], v[70:73], v[138:141], v[154:157]
	v_mfma_f32_16x16x32_bf16 v[126:129], v[58:61], v[146:149], v[126:129]
	v_mfma_f32_16x16x32_bf16 v[122:125], v[70:73], v[146:149], v[122:125]
	v_mfma_f32_16x16x32_bf16 v[110:113], v[58:61], v[162:165], v[110:113]
	v_mfma_f32_16x16x32_bf16 v[106:109], v[70:73], v[162:165], v[106:109]
	v_mfma_f32_16x16x32_bf16 v[94:97], v[58:61], v[170:173], v[94:97]
	v_mfma_f32_16x16x32_bf16 v[90:93], v[70:73], v[170:173], v[90:93]
	v_mfma_f32_16x16x32_bf16 v[158:161], v[62:65], v[142:145], v[158:161]
	v_mfma_f32_16x16x32_bf16 v[154:157], v[74:77], v[142:145], v[154:157]
	v_mfma_f32_16x16x32_bf16 v[126:129], v[62:65], v[150:153], v[126:129]
	v_mfma_f32_16x16x32_bf16 v[122:125], v[74:77], v[150:153], v[122:125]
	v_mfma_f32_16x16x32_bf16 v[110:113], v[62:65], v[166:169], v[110:113]
	v_mfma_f32_16x16x32_bf16 v[106:109], v[74:77], v[166:169], v[106:109]
	v_mfma_f32_16x16x32_bf16 v[94:97], v[62:65], v[184:187], v[94:97]
	v_mfma_f32_16x16x32_bf16 v[90:93], v[74:77], v[184:187], v[90:93]
	s_barrier
	s_add_i32 s44, 0, 0x1c000
	s_add_i32 s45, s52, s20
	s_mov_b32 m0, s45
	ds_read_b128 v[188:191], v249 offset:49152
	ds_read_b128 v[220:223], v249 offset:50176
	ds_read_b128 v[224:227], v249 offset:51200
	ds_read_b128 v[228:231], v249 offset:52224
	global_load_lds_dwordx4 v0, s[98:99]
	s_add_i32 m0, s45, 0x2000
	s_nop 0
	global_load_lds_dwordx4 v174, s[98:99]
	s_barrier
	s_waitcnt lgkmcnt(0)
	v_mfma_f32_16x16x32_bf16 v[134:137], v[188:191], v[138:141], v[134:137]
	v_mfma_f32_16x16x32_bf16 v[130:133], v[224:227], v[138:141], v[130:133]
	v_mfma_f32_16x16x32_bf16 v[118:121], v[188:191], v[146:149], v[118:121]
	v_mfma_f32_16x16x32_bf16 v[114:117], v[224:227], v[146:149], v[114:117]
	v_mfma_f32_16x16x32_bf16 v[102:105], v[188:191], v[162:165], v[102:105]
	v_mfma_f32_16x16x32_bf16 v[98:101], v[224:227], v[162:165], v[98:101]
	v_mfma_f32_16x16x32_bf16 v[86:89], v[188:191], v[170:173], v[86:89]
	v_mfma_f32_16x16x32_bf16 v[82:85], v[224:227], v[170:173], v[82:85]
	v_mfma_f32_16x16x32_bf16 v[134:137], v[220:223], v[142:145], v[134:137]
	v_mfma_f32_16x16x32_bf16 v[130:133], v[228:231], v[142:145], v[130:133]
	v_mfma_f32_16x16x32_bf16 v[118:121], v[220:223], v[150:153], v[118:121]
	v_mfma_f32_16x16x32_bf16 v[114:117], v[228:231], v[150:153], v[114:117]
	v_mfma_f32_16x16x32_bf16 v[102:105], v[220:223], v[166:169], v[102:105]
	v_mfma_f32_16x16x32_bf16 v[98:101], v[228:231], v[166:169], v[98:101]
	v_mfma_f32_16x16x32_bf16 v[86:89], v[220:223], v[184:187], v[86:89]
	v_mfma_f32_16x16x32_bf16 v[82:85], v[228:231], v[184:187], v[82:85]
	s_barrier
; #define PG8_STAGE(bufoff, gbase, voff) do { _Pragma("unroll") for (int _i = 0; _i < 2; ++_i) \
;         __builtin_amdgcn_global_load_lds((const unsigned*)((const char*)(gbase) + (voff)[_i]), (LAS unsigned*)(lds + (bufoff) + ldsw + _i * 8192), 16, 0, 0); } while (0)
; #define PG8_LDA(dst, b, h) do { _Pragma("unroll") for (int m = 0; m < 4; ++m) _Pragma("unroll") for (int k = 0; k < 2; ++k) dst[m][k] = *(const LAS bf16x8*)(lds + PG8_SA(b, h) + aoff + m * 2048 + k * 1024); } while (0)
; #define PG8_MMA(ai, bj, At, Bt) do { __builtin_amdgcn_s_setprio(1); _Pragma("unroll") for (int m = 0; m < 4; ++m) _Pragma("unroll") for (int n = 0; n < 2; ++n) _Pragma("unroll") for (int k = 0; k < 2; ++k) \
;         acc[ai][bj][m][n] = __builtin_amdgcn_mfma_f32_16x16x32_bf16(Bt[n][k], At[m][k], acc[ai][bj][m][n], 0, 0, 0); __builtin_amdgcn_s_setprio(0); } while (0)
; #define PG8_WAIT_V(n) asm volatile("s_waitcnt vmcnt(" #n ")" ::: "memory")
; #define PG8_WAIT_L(n) asm volatile("s_waitcnt lgkmcnt(" #n ")" ::: "memory")
; #define PG8_BAR __builtin_amdgcn_s_barrier()
; #define PG8_SCHED __builtin_amdgcn_sched_barrier(0)
;     template <int mode> __device__ __forceinline__ void run(const f32x4 (&acc)[2][2][4][2], const Unit& u, int wr, int wc, int fr, int fq, const LAS float* sc) const {
;     ...
;             const int col0 = u.pn * BM + wc * 32 + 8 * fq;
;             float sA = 1.f, sB = 1.f;
;             if (mode == 4) scales2(u, wr, fr, fq, sA, sB);
;             f32x4 bvv[4];
; #pragma unroll
;             for (int q = 0; q < 4; ++q) bvv[q] = (mode != 4 && bias) ? *(const f32x4*)(bias + col0 + (q >> 1) * HALF + (q & 1) * 4) : (f32x4){0.f, 0.f, 0.f, 0.f};
; template <int MODE, class EpiT, class Sched>
; __device__ __forceinline__ void gemm_phase(LAS unsigned char* lds, const Gemm g, const Sched& S, const EpiT& E) {
;     ...
;             PG8_LDA(At, 1, 1); PG8_STAGE(PG8_SA(1, 0), a3, voffA);
;             PG8_BAR; PG8_WAIT_L(0); PG8_MMA(1, 0, At, B0); PG8_BAR; PG8_SCHED;
;             PG8_STAGE(PG8_SB(1, 1), b3 + hstep, voffB);
;             PG8_WAIT_V(6); PG8_BAR; PG8_MMA(1, 1, At, B1); PG8_BAR;
;         }
	s_mov_b32 m0, s61
	ds_read_b128 v[138:141], v196 offset:49152
	ds_read_b128 v[142:145], v196 offset:50176
	ds_read_b128 v[146:149], v196 offset:51200
	ds_read_b128 v[150:153], v196 offset:52224
	ds_read_b128 v[162:165], v196 offset:53248
	ds_read_b128 v[166:169], v196 offset:54272
	ds_read_b128 v[170:173], v196 offset:55296
	ds_read_b128 v[184:187], v196 offset:56320
	global_load_lds_dwordx4 v0, s[100:101]
	s_mov_b32 m0, s74
	s_nop 0
	global_load_lds_dwordx4 v174, s[100:101]
	s_barrier
	s_waitcnt lgkmcnt(0)
	v_mfma_f32_16x16x32_bf16 v[78:81], v[58:61], v[138:141], v[78:81]
	v_mfma_f32_16x16x32_bf16 v[66:69], v[70:73], v[138:141], v[66:69]
	v_mfma_f32_16x16x32_bf16 v[46:49], v[58:61], v[146:149], v[46:49]
	v_mfma_f32_16x16x32_bf16 v[42:45], v[70:73], v[146:149], v[42:45]
	v_mfma_f32_16x16x32_bf16 v[30:33], v[58:61], v[162:165], v[30:33]
	v_mfma_f32_16x16x32_bf16 v[26:29], v[70:73], v[162:165], v[26:29]
	v_mfma_f32_16x16x32_bf16 v[14:17], v[58:61], v[170:173], v[14:17]
	v_mfma_f32_16x16x32_bf16 v[10:13], v[70:73], v[170:173], v[10:13]
	v_mfma_f32_16x16x32_bf16 v[78:81], v[62:65], v[142:145], v[78:81]
	v_mfma_f32_16x16x32_bf16 v[66:69], v[74:77], v[142:145], v[66:69]
	v_mfma_f32_16x16x32_bf16 v[46:49], v[62:65], v[150:153], v[46:49]
	v_mfma_f32_16x16x32_bf16 v[42:45], v[74:77], v[150:153], v[42:45]
	v_mfma_f32_16x16x32_bf16 v[30:33], v[62:65], v[166:169], v[30:33]
	v_mfma_f32_16x16x32_bf16 v[26:29], v[74:77], v[166:169], v[26:29]
	v_mfma_f32_16x16x32_bf16 v[14:17], v[62:65], v[184:187], v[14:17]
	v_mfma_f32_16x16x32_bf16 v[10:13], v[74:77], v[184:187], v[10:13]
	s_barrier
	s_add_i32 s44, s44, s20
	s_add_u32 s98, s98, s38
	s_addc_u32 s99, s99, 0
	s_mov_b32 m0, s44
	s_nop 0
	global_load_lds_dwordx4 v0, s[98:99]
	s_add_i32 m0, s44, 0x2000
	s_nop 0
	global_load_lds_dwordx4 v174, s[98:99]
	s_waitcnt vmcnt(6)
	s_barrier
	v_mfma_f32_16x16x32_bf16 v[54:57], v[188:191], v[138:141], v[54:57]
	v_mfma_f32_16x16x32_bf16 v[50:53], v[224:227], v[138:141], v[50:53]
	v_mfma_f32_16x16x32_bf16 v[38:41], v[188:191], v[146:149], v[38:41]
	v_mfma_f32_16x16x32_bf16 v[34:37], v[224:227], v[146:149], v[34:37]
	v_mfma_f32_16x16x32_bf16 v[22:25], v[188:191], v[162:165], v[22:25]
	v_mfma_f32_16x16x32_bf16 v[18:21], v[224:227], v[162:165], v[18:21]
	v_mfma_f32_16x16x32_bf16 v[6:9], v[188:191], v[170:173], v[6:9]
	v_mfma_f32_16x16x32_bf16 v[2:5], v[224:227], v[170:173], v[2:5]
	v_mfma_f32_16x16x32_bf16 v[54:57], v[220:223], v[142:145], v[54:57]
	v_mfma_f32_16x16x32_bf16 v[50:53], v[228:231], v[142:145], v[50:53]
	v_mfma_f32_16x16x32_bf16 v[38:41], v[220:223], v[150:153], v[38:41]
	v_mfma_f32_16x16x32_bf16 v[34:37], v[228:231], v[150:153], v[34:37]
	v_mfma_f32_16x16x32_bf16 v[22:25], v[220:223], v[166:169], v[22:25]
	v_mfma_f32_16x16x32_bf16 v[18:21], v[228:231], v[166:169], v[18:21]
	v_mfma_f32_16x16x32_bf16 v[6:9], v[220:223], v[184:187], v[6:9]
	v_mfma_f32_16x16x32_bf16 v[2:5], v[228:231], v[184:187], v[2:5]
	s_barrier
	s_add_u32 s4, s4, 0x100
	s_addc_u32 s5, s5, 0
	s_add_u32 s89, s89, 0x100
	s_addc_u32 s90, s90, 0
	s_cmp_ge_u32 vcc_lo, s60
	s_mov_b32 s44, vcc_lo
	s_cbranch_scc0 .LBB0_195
	v_lshl_or_b32 v186, s24, 8, v195
	v_ashrrev_i32_e32 v187, 31, v186
	v_mov_b32_e32 v70, 0
	v_cndmask_b32_e64 v58, 0, 1, s[78:79]
	v_lshl_add_u64 v[138:139], v[186:187], 2, s[12:13]
	v_cmp_ne_u32_e64 s[44:45], 1, v58
	s_andn2_b64 vcc, exec, s[78:79]
	v_mov_b32_e32 v74, 0
	v_mov_b32_e32 v75, v70
	v_mov_b32_e32 v184, 0
	v_mov_b32_e32 v185, v70
	s_cbranch_vccnz .LBB0_198
	global_load_dwordx4 v[74:77], v[138:139], off
	s_waitcnt vmcnt(0)
	v_mov_b32_e32 v184, v76
	v_mov_b32_e32 v185, v77
